# P6 K-loop as well: 12 of the 16 LDS-DMA loads per loop body in saddr form (no 64-bit VALU address add)
# baseline (speedup 1.0000x reference)
.LBB0_529:
	ds_read_b128 v[96:99], v179
	ds_read_b128 v[100:103], v179 offset:1024
	ds_read_b128 v[104:107], v179 offset:2048
	ds_read_b128 v[108:111], v179 offset:3072
	ds_read_b128 v[156:159], v180
	ds_read_b128 v[160:163], v180 offset:1024
	ds_read_b128 v[164:167], v180 offset:2048
	ds_read_b128 v[168:171], v180 offset:3072
	s_add_u32 s26, s2, 0xfff80080
	s_addc_u32 s27, s3, -1
	s_cmp_eq_u32 s70, 28
	s_cselect_b32 s29, s68, s27
	s_cselect_b32 s28, s69, s26
	s_cselect_b32 s27, s5, s25
	s_cselect_b32 s26, s4, s24
	s_add_u32 s100, s26, 0x80
	s_addc_u32 s101, s27, 0
	s_add_i32 m0, s34, 0xc000
	ds_read_b128 v[172:175], v181
	ds_read_b128 v[184:187], v181 offset:1024
	ds_read_b128 v[188:191], v181 offset:2048
	ds_read_b128 v[194:197], v181 offset:3072
	ds_read_b128 v[198:201], v181 offset:4096
	ds_read_b128 v[202:205], v181 offset:5120
	ds_read_b128 v[206:209], v181 offset:6144
	ds_read_b128 v[210:213], v181 offset:7168
	global_load_lds_dwordx4 v144, s[2:3]
	s_add_i32 m0, s34, 0xe000
	s_nop 0
	global_load_lds_dwordx4 v146, s[2:3]
	s_waitcnt vmcnt(8)
	s_waitcnt lgkmcnt(0)
	s_barrier
	s_setprio 1
	s_waitcnt lgkmcnt(0)
	v_mfma_f32_16x16x32_bf16 v[140:143], v[96:99], v[172:175], v[140:143]
	v_mfma_f32_16x16x32_bf16 v[136:139], v[104:107], v[172:175], v[136:139]
	v_mfma_f32_16x16x32_bf16 v[124:127], v[96:99], v[188:191], v[124:127]
	v_mfma_f32_16x16x32_bf16 v[120:123], v[104:107], v[188:191], v[120:123]
	v_mfma_f32_16x16x32_bf16 v[92:95], v[96:99], v[198:201], v[92:95]
	v_mfma_f32_16x16x32_bf16 v[88:91], v[104:107], v[198:201], v[88:91]
	v_mfma_f32_16x16x32_bf16 v[76:79], v[96:99], v[206:209], v[76:79]
	v_mfma_f32_16x16x32_bf16 v[72:75], v[104:107], v[206:209], v[72:75]
	v_mfma_f32_16x16x32_bf16 v[140:143], v[100:103], v[184:187], v[140:143]
	v_mfma_f32_16x16x32_bf16 v[136:139], v[108:111], v[184:187], v[136:139]
	v_mfma_f32_16x16x32_bf16 v[124:127], v[100:103], v[194:197], v[124:127]
	v_mfma_f32_16x16x32_bf16 v[120:123], v[108:111], v[194:197], v[120:123]
	v_mfma_f32_16x16x32_bf16 v[92:95], v[100:103], v[202:205], v[92:95]
	v_mfma_f32_16x16x32_bf16 v[88:91], v[108:111], v[202:205], v[88:91]
	v_mfma_f32_16x16x32_bf16 v[76:79], v[100:103], v[210:213], v[76:79]
	v_mfma_f32_16x16x32_bf16 v[72:75], v[108:111], v[210:213], v[72:75]
	s_setprio 0
	s_setprio 1
	v_mfma_f32_16x16x32_bf16 v[132:135], v[156:159], v[172:175], v[132:135]
	v_mfma_f32_16x16x32_bf16 v[128:131], v[164:167], v[172:175], v[128:131]
	v_mfma_f32_16x16x32_bf16 v[116:119], v[156:159], v[188:191], v[116:119]
	v_mfma_f32_16x16x32_bf16 v[112:115], v[164:167], v[188:191], v[112:115]
	v_mfma_f32_16x16x32_bf16 v[84:87], v[156:159], v[198:201], v[84:87]
	v_mfma_f32_16x16x32_bf16 v[80:83], v[164:167], v[198:201], v[80:83]
	v_mfma_f32_16x16x32_bf16 v[68:71], v[156:159], v[206:209], v[68:71]
	v_mfma_f32_16x16x32_bf16 v[64:67], v[164:167], v[206:209], v[64:67]
	v_mfma_f32_16x16x32_bf16 v[132:135], v[160:163], v[184:187], v[132:135]
	v_mfma_f32_16x16x32_bf16 v[128:131], v[168:171], v[184:187], v[128:131]
	v_mfma_f32_16x16x32_bf16 v[116:119], v[160:163], v[194:197], v[116:119]
	v_mfma_f32_16x16x32_bf16 v[112:115], v[168:171], v[194:197], v[112:115]
	v_mfma_f32_16x16x32_bf16 v[84:87], v[160:163], v[202:205], v[84:87]
	v_mfma_f32_16x16x32_bf16 v[80:83], v[168:171], v[202:205], v[80:83]
	v_mfma_f32_16x16x32_bf16 v[68:71], v[160:163], v[210:213], v[68:71]
	v_mfma_f32_16x16x32_bf16 v[64:67], v[168:171], v[210:213], v[64:67]
	s_setprio 0
	s_barrier
	s_add_i32 s71, s54, s1
	s_mov_b32 m0, s71
	ds_read_b128 v[172:175], v181 offset:16384
	ds_read_b128 v[184:187], v181 offset:17408
	ds_read_b128 v[188:191], v181 offset:18432
	ds_read_b128 v[194:197], v181 offset:19456
	ds_read_b128 v[198:201], v181 offset:20480
	ds_read_b128 v[202:205], v181 offset:21504
	ds_read_b128 v[206:209], v181 offset:22528
	ds_read_b128 v[210:213], v181 offset:23552
	global_load_lds_dwordx4 v150, s[26:27]
	s_add_i32 m0, s71, 0x2000
	s_add_u32 s72, s26, 0x80000
	s_addc_u32 s73, s27, 0
	s_add_i32 s71, s55, s1
	global_load_lds_dwordx4 v154, s[26:27]
	s_mov_b32 m0, s71
	v_lshl_add_u64 v[220:221], s[28:29], 0, v[152:153]
	global_load_lds_dwordx4 v150, s[72:73]
	s_add_i32 m0, s71, 0x2000
	s_nop 0
	global_load_lds_dwordx4 v154, s[72:73]
	v_lshl_add_u64 v[218:219], s[28:29], 0, v[148:149]
	s_mov_b32 m0, s34
	s_nop 0
	global_load_lds_dwordx4 v[218:219], off
	s_mov_b32 m0, s35
	s_nop 0
	global_load_lds_dwordx4 v[220:221], off
	s_waitcnt vmcnt(8)
	s_waitcnt lgkmcnt(0)
	s_barrier
	s_setprio 1
	s_waitcnt lgkmcnt(0)
	v_mfma_f32_16x16x32_bf16 v[60:63], v[96:99], v[172:175], v[60:63]
	v_mfma_f32_16x16x32_bf16 v[56:59], v[104:107], v[172:175], v[56:59]
	v_mfma_f32_16x16x32_bf16 v[44:47], v[96:99], v[188:191], v[44:47]
	v_mfma_f32_16x16x32_bf16 v[40:43], v[104:107], v[188:191], v[40:43]
	v_mfma_f32_16x16x32_bf16 v[28:31], v[96:99], v[198:201], v[28:31]
	v_mfma_f32_16x16x32_bf16 v[24:27], v[104:107], v[198:201], v[24:27]
	v_mfma_f32_16x16x32_bf16 v[12:15], v[96:99], v[206:209], v[12:15]
	v_mfma_f32_16x16x32_bf16 v[8:11], v[104:107], v[206:209], v[8:11]
	v_mfma_f32_16x16x32_bf16 v[60:63], v[100:103], v[184:187], v[60:63]
	v_mfma_f32_16x16x32_bf16 v[56:59], v[108:111], v[184:187], v[56:59]
	v_mfma_f32_16x16x32_bf16 v[44:47], v[100:103], v[194:197], v[44:47]
	v_mfma_f32_16x16x32_bf16 v[40:43], v[108:111], v[194:197], v[40:43]
	v_mfma_f32_16x16x32_bf16 v[28:31], v[100:103], v[202:205], v[28:31]
	v_mfma_f32_16x16x32_bf16 v[24:27], v[108:111], v[202:205], v[24:27]
	v_mfma_f32_16x16x32_bf16 v[12:15], v[100:103], v[210:213], v[12:15]
	v_mfma_f32_16x16x32_bf16 v[8:11], v[108:111], v[210:213], v[8:11]
	s_setprio 0
	s_setprio 1
	v_mfma_f32_16x16x32_bf16 v[52:55], v[156:159], v[172:175], v[52:55]
	v_mfma_f32_16x16x32_bf16 v[48:51], v[164:167], v[172:175], v[48:51]
	v_mfma_f32_16x16x32_bf16 v[36:39], v[156:159], v[188:191], v[36:39]
	v_mfma_f32_16x16x32_bf16 v[32:35], v[164:167], v[188:191], v[32:35]
	v_mfma_f32_16x16x32_bf16 v[20:23], v[156:159], v[198:201], v[20:23]
	v_mfma_f32_16x16x32_bf16 v[16:19], v[164:167], v[198:201], v[16:19]
	v_mfma_f32_16x16x32_bf16 v[4:7], v[156:159], v[206:209], v[4:7]
	v_mfma_f32_16x16x32_bf16 v[0:3], v[164:167], v[206:209], v[0:3]
	v_mfma_f32_16x16x32_bf16 v[52:55], v[160:163], v[184:187], v[52:55]
	v_mfma_f32_16x16x32_bf16 v[48:51], v[168:171], v[184:187], v[48:51]
	v_mfma_f32_16x16x32_bf16 v[36:39], v[160:163], v[194:197], v[36:39]
	v_mfma_f32_16x16x32_bf16 v[32:35], v[168:171], v[194:197], v[32:35]
	v_mfma_f32_16x16x32_bf16 v[20:23], v[160:163], v[202:205], v[20:23]
	v_mfma_f32_16x16x32_bf16 v[16:19], v[168:171], v[202:205], v[16:19]
	v_mfma_f32_16x16x32_bf16 v[4:7], v[160:163], v[210:213], v[4:7]
	v_mfma_f32_16x16x32_bf16 v[0:3], v[168:171], v[210:213], v[0:3]
	s_setprio 0
	s_barrier
	s_add_i32 s71, 0, 0x18000
	s_add_i32 s72, 0, 0x1c000
	v_add_u32_e32 v108, s71, v178
	v_add_u32_e32 v168, s72, v178
	ds_read_b128 v[96:99], v108
	ds_read_b128 v[100:103], v108 offset:1024
	ds_read_b128 v[104:107], v108 offset:2048
	ds_read_b128 v[108:111], v108 offset:3072
	ds_read_b128 v[156:159], v168
	ds_read_b128 v[160:163], v168 offset:1024
	ds_read_b128 v[164:167], v168 offset:2048
	ds_read_b128 v[168:171], v168 offset:3072
	s_add_u32 s28, s28, 0x80000
	s_addc_u32 s29, s29, 0
	s_mov_b32 m0, s36
	ds_read_b128 v[172:175], v181 offset:32768
	ds_read_b128 v[184:187], v181 offset:33792
	ds_read_b128 v[188:191], v181 offset:34816
	ds_read_b128 v[194:197], v181 offset:35840
	ds_read_b128 v[198:201], v181 offset:36864
	ds_read_b128 v[202:205], v181 offset:37888
	ds_read_b128 v[206:209], v181 offset:38912
	ds_read_b128 v[210:213], v181 offset:39936
	global_load_lds_dwordx4 v148, s[28:29]
	s_mov_b32 m0, s37
	s_nop 0
	global_load_lds_dwordx4 v152, s[28:29]
	s_waitcnt vmcnt(8)
	s_waitcnt lgkmcnt(0)
	s_barrier
	s_setprio 1
	s_waitcnt lgkmcnt(0)
	v_mfma_f32_16x16x32_bf16 v[140:143], v[96:99], v[172:175], v[140:143]
	v_mfma_f32_16x16x32_bf16 v[136:139], v[104:107], v[172:175], v[136:139]
	v_mfma_f32_16x16x32_bf16 v[124:127], v[96:99], v[188:191], v[124:127]
	v_mfma_f32_16x16x32_bf16 v[120:123], v[104:107], v[188:191], v[120:123]
	v_mfma_f32_16x16x32_bf16 v[92:95], v[96:99], v[198:201], v[92:95]
	v_mfma_f32_16x16x32_bf16 v[88:91], v[104:107], v[198:201], v[88:91]
	v_mfma_f32_16x16x32_bf16 v[76:79], v[96:99], v[206:209], v[76:79]
	v_mfma_f32_16x16x32_bf16 v[72:75], v[104:107], v[206:209], v[72:75]
	v_mfma_f32_16x16x32_bf16 v[140:143], v[100:103], v[184:187], v[140:143]
	v_mfma_f32_16x16x32_bf16 v[136:139], v[108:111], v[184:187], v[136:139]
	v_mfma_f32_16x16x32_bf16 v[124:127], v[100:103], v[194:197], v[124:127]
	v_mfma_f32_16x16x32_bf16 v[120:123], v[108:111], v[194:197], v[120:123]
	v_mfma_f32_16x16x32_bf16 v[92:95], v[100:103], v[202:205], v[92:95]
	v_mfma_f32_16x16x32_bf16 v[88:91], v[108:111], v[202:205], v[88:91]
	v_mfma_f32_16x16x32_bf16 v[76:79], v[100:103], v[210:213], v[76:79]
	v_mfma_f32_16x16x32_bf16 v[72:75], v[108:111], v[210:213], v[72:75]
	s_setprio 0
	s_setprio 1
	v_mfma_f32_16x16x32_bf16 v[132:135], v[156:159], v[172:175], v[132:135]
	v_mfma_f32_16x16x32_bf16 v[128:131], v[164:167], v[172:175], v[128:131]
	v_mfma_f32_16x16x32_bf16 v[116:119], v[156:159], v[188:191], v[116:119]
	v_mfma_f32_16x16x32_bf16 v[112:115], v[164:167], v[188:191], v[112:115]
	v_mfma_f32_16x16x32_bf16 v[84:87], v[156:159], v[198:201], v[84:87]
	v_mfma_f32_16x16x32_bf16 v[80:83], v[164:167], v[198:201], v[80:83]
	v_mfma_f32_16x16x32_bf16 v[68:71], v[156:159], v[206:209], v[68:71]
	v_mfma_f32_16x16x32_bf16 v[64:67], v[164:167], v[206:209], v[64:67]
	v_mfma_f32_16x16x32_bf16 v[132:135], v[160:163], v[184:187], v[132:135]
	v_mfma_f32_16x16x32_bf16 v[128:131], v[168:171], v[184:187], v[128:131]
	v_mfma_f32_16x16x32_bf16 v[116:119], v[160:163], v[194:197], v[116:119]
	v_mfma_f32_16x16x32_bf16 v[112:115], v[168:171], v[194:197], v[112:115]
	v_mfma_f32_16x16x32_bf16 v[84:87], v[160:163], v[202:205], v[84:87]
	v_mfma_f32_16x16x32_bf16 v[80:83], v[168:171], v[202:205], v[80:83]
	v_mfma_f32_16x16x32_bf16 v[68:71], v[160:163], v[210:213], v[68:71]
	v_mfma_f32_16x16x32_bf16 v[64:67], v[168:171], v[210:213], v[64:67]
	s_setprio 0
	s_barrier
	s_add_i32 s28, s71, s1
	s_mov_b32 m0, s28
	ds_read_b128 v[172:175], v181 offset:49152
	ds_read_b128 v[184:187], v181 offset:50176
	ds_read_b128 v[188:191], v181 offset:51200
	ds_read_b128 v[194:197], v181 offset:52224
	ds_read_b128 v[198:201], v181 offset:53248
	ds_read_b128 v[202:205], v181 offset:54272
	ds_read_b128 v[206:209], v181 offset:55296
	ds_read_b128 v[210:213], v181 offset:56320
	global_load_lds_dwordx4 v150, s[100:101]
	s_add_i32 m0, s28, 0x2000
	s_add_u32 s26, s26, 0x80080
	s_addc_u32 s27, s27, 0
	s_add_i32 s28, s72, s1
	global_load_lds_dwordx4 v154, s[100:101]
	s_mov_b32 m0, s28
	s_nop 0
	global_load_lds_dwordx4 v150, s[26:27]
	s_add_i32 m0, s28, 0x2000
	s_nop 0
	global_load_lds_dwordx4 v154, s[26:27]
	v_lshl_add_u64 v[214:215], v[218:219], 0, s[14:15]
	s_mov_b32 m0, s43
	s_nop 0
	global_load_lds_dwordx4 v[214:215], off
	v_lshl_add_u64 v[214:215], v[220:221], 0, s[14:15]
	s_mov_b32 m0, s48
	s_nop 0
	global_load_lds_dwordx4 v[214:215], off
	s_waitcnt vmcnt(8)
	s_waitcnt lgkmcnt(0)
	s_barrier
	s_setprio 1
	s_waitcnt lgkmcnt(0)
	v_mfma_f32_16x16x32_bf16 v[60:63], v[96:99], v[172:175], v[60:63]
	v_mfma_f32_16x16x32_bf16 v[56:59], v[104:107], v[172:175], v[56:59]
	v_mfma_f32_16x16x32_bf16 v[44:47], v[96:99], v[188:191], v[44:47]
	v_mfma_f32_16x16x32_bf16 v[40:43], v[104:107], v[188:191], v[40:43]
	v_mfma_f32_16x16x32_bf16 v[28:31], v[96:99], v[198:201], v[28:31]
	v_mfma_f32_16x16x32_bf16 v[24:27], v[104:107], v[198:201], v[24:27]
	v_mfma_f32_16x16x32_bf16 v[12:15], v[96:99], v[206:209], v[12:15]
	v_mfma_f32_16x16x32_bf16 v[8:11], v[104:107], v[206:209], v[8:11]
	v_mfma_f32_16x16x32_bf16 v[60:63], v[100:103], v[184:187], v[60:63]
	v_mfma_f32_16x16x32_bf16 v[56:59], v[108:111], v[184:187], v[56:59]
	v_mfma_f32_16x16x32_bf16 v[44:47], v[100:103], v[194:197], v[44:47]
	v_mfma_f32_16x16x32_bf16 v[40:43], v[108:111], v[194:197], v[40:43]
	v_mfma_f32_16x16x32_bf16 v[28:31], v[100:103], v[202:205], v[28:31]
	v_mfma_f32_16x16x32_bf16 v[24:27], v[108:111], v[202:205], v[24:27]
	v_mfma_f32_16x16x32_bf16 v[12:15], v[100:103], v[210:213], v[12:15]
	v_mfma_f32_16x16x32_bf16 v[8:11], v[108:111], v[210:213], v[8:11]
	s_setprio 0
	s_setprio 1
	v_mfma_f32_16x16x32_bf16 v[52:55], v[156:159], v[172:175], v[52:55]
	v_mfma_f32_16x16x32_bf16 v[48:51], v[164:167], v[172:175], v[48:51]
	v_mfma_f32_16x16x32_bf16 v[36:39], v[156:159], v[188:191], v[36:39]
	v_mfma_f32_16x16x32_bf16 v[32:35], v[164:167], v[188:191], v[32:35]
	v_mfma_f32_16x16x32_bf16 v[20:23], v[156:159], v[198:201], v[20:23]
	v_mfma_f32_16x16x32_bf16 v[16:19], v[164:167], v[198:201], v[16:19]
	v_mfma_f32_16x16x32_bf16 v[4:7], v[156:159], v[206:209], v[4:7]
	v_mfma_f32_16x16x32_bf16 v[0:3], v[164:167], v[206:209], v[0:3]
	v_mfma_f32_16x16x32_bf16 v[52:55], v[160:163], v[184:187], v[52:55]
	v_mfma_f32_16x16x32_bf16 v[48:51], v[168:171], v[184:187], v[48:51]
	v_mfma_f32_16x16x32_bf16 v[36:39], v[160:163], v[194:197], v[36:39]
	v_mfma_f32_16x16x32_bf16 v[32:35], v[168:171], v[194:197], v[32:35]
	v_mfma_f32_16x16x32_bf16 v[20:23], v[160:163], v[202:205], v[20:23]
	v_mfma_f32_16x16x32_bf16 v[16:19], v[168:171], v[202:205], v[16:19]
	v_mfma_f32_16x16x32_bf16 v[4:7], v[160:163], v[210:213], v[4:7]
	v_mfma_f32_16x16x32_bf16 v[0:3], v[168:171], v[210:213], v[0:3]
	s_setprio 0
	s_barrier
	s_add_i32 s70, s70, 2
	s_add_u32 s2, s2, 0x100
	s_addc_u32 s3, s3, 0
	s_add_u32 s24, s24, 0x100
	s_addc_u32 s25, s25, 0
	s_cmp_gt_u32 s70, 29
	s_cbranch_scc0 .LBB0_529
	s_and_b64 vcc, exec, s[18:19]
	s_cbranch_vccz .LBB0_532
	s_barrier
